# guarded kernel + mLSTM chunk: batched LDS reads around barrier B2 (ssq partials, last K pair, four output-gain reads) with counted waits
# speedup vs baseline: 1.0040x; 1.0028x over previous
; #define LAS __attribute__((address_space(3)))
; DI float lo_f(unsigned u) { return __uint_as_float(u << 16); }
; DI float hi_f(unsigned u) { return __uint_as_float(u & 0xffff0000u); }
; DI unsigned pk2(float lo, float hi) { return pg8::cvt_pk_bf16(lo, hi); }
; DI void mlstm_seq(LAS unsigned char* lds, const bf16* P, const float* IFg, bf16* Hout, const float* conv_w, const float* conv_b, const float* mlg, int seq) {
;     ...
; #pragma unroll
;         for (int rq = 0; rq < 4; ++rq) { const int dv = 32 * dvs + 8 * rq + 4 * hh; const f32x4 gl = *(const LAS f32x4*)(mlgl + dv);
;             const float o0 = hv[4 * rq] * rstd * gl[0] * lo_f(og[rq].x), o1 = hv[4 * rq + 1] * rstd * gl[1] * hi_f(og[rq].x), o2 = hv[4 * rq + 2] * rstd * gl[2] * lo_f(og[rq].y), o3 = hv[4 * rq + 3] * rstd * gl[3] * hi_f(og[rq].y);
;             v2u w; w.x = pk2(o0, o1); w.y = pk2(o2, o3); *(v2u*)(Hout + row * 1024 + hd * 128 + dv) = w;
;             v2u cw; cw.x = pk2(Cst[4 * rq], Cst[4 * rq + 1]); cw.y = pk2(Cst[4 * rq + 2], Cst[4 * rq + 3]);
;             *(LAS v2u*)(Cimg + (32 * th + r32) * 320 + 2 * dv) = cw; }
;         if (wv == 5) { float s = 0.f;
; #pragma unroll
;             for (int w = 0; w < 8; ++w) s += npart[w * 64 + lane];
;             n_reg = dec * n_reg + s; nvec[lane] = n_reg; }
.Lhw_done:
	ds_read_b128 v[2:5], v204
	ds_read_b128 v[10:13], v206
	ds_read_b128 v[92:95], v207
	ds_read_b128 v[96:99], v205
	v_mul_f32_e32 v0, v0, v8
	s_waitcnt lgkmcnt(3)
	v_mul_f32_e32 v0, v2, v0
	v_lshlrev_b32_e32 v2, 16, v152
	v_mul_f32_e32 v0, v0, v2
	v_mul_f32_e32 v2, v14, v8
	v_mul_f32_e32 v2, v3, v2
	v_and_b32_e32 v3, 0xffff0000, v152
	v_mul_f32_e32 v2, v2, v3
	v_mul_f32_e32 v3, v48, v8
	v_mul_f32_e32 v3, v4, v3
	v_lshlrev_b32_e32 v4, 16, v153
	v_mul_f32_e32 v3, v3, v4
	v_mul_f32_e32 v4, v49, v8
	v_mul_f32_e32 v4, v5, v4
	v_and_b32_e32 v5, 0xffff0000, v153
	v_mul_f32_e32 v4, v4, v5
	v_cvt_pk_bf16_f32 v152, v0, v2
	v_cvt_pk_bf16_f32 v153, v3, v4
	v_add_u32_e32 v0, v140, v208
	v_cvt_pk_bf16_f32 v2, v16, v17
	v_cvt_pk_bf16_f32 v3, v18, v19
	ds_write_b64 v0, v[2:3] offset:51200
	v_mul_f32_e32 v0, v40, v8
	s_waitcnt lgkmcnt(3)
	v_mul_f32_e32 v0, v10, v0
	v_lshlrev_b32_e32 v2, 16, v148
	v_mul_f32_e32 v0, v0, v2
	v_mul_f32_e32 v2, v41, v8
	v_mul_f32_e32 v2, v11, v2
	v_and_b32_e32 v3, 0xffff0000, v148
	v_mul_f32_e32 v2, v2, v3
	v_mul_f32_e32 v3, v42, v8
	v_mul_f32_e32 v3, v12, v3
	v_lshlrev_b32_e32 v4, 16, v149
	v_mul_f32_e32 v3, v3, v4
	v_mul_f32_e32 v4, v43, v8
	v_mul_f32_e32 v4, v13, v4
	v_and_b32_e32 v5, 0xffff0000, v149
	v_mul_f32_e32 v4, v4, v5
	v_cvt_pk_bf16_f32 v42, v0, v2
	v_cvt_pk_bf16_f32 v43, v3, v4
	v_mov_b32_e32 v40, v152
	v_mov_b32_e32 v41, v153
	v_cvt_pk_bf16_f32 v2, v20, v21
	v_cvt_pk_bf16_f32 v3, v22, v23
	ds_write_b64 v229, v[2:3] offset:51200
	v_mul_f32_e32 v0, v36, v8
	s_waitcnt lgkmcnt(3)
	v_mul_f32_e32 v0, v92, v0
	v_lshlrev_b32_e32 v2, 16, v146
	v_mul_f32_e32 v0, v0, v2
	v_mul_f32_e32 v2, v37, v8
	v_mul_f32_e32 v2, v93, v2
	v_and_b32_e32 v3, 0xffff0000, v146
	v_mul_f32_e32 v2, v2, v3
	v_mul_f32_e32 v3, v38, v8
	v_mul_f32_e32 v3, v94, v3
	v_lshlrev_b32_e32 v4, 16, v147
	v_mul_f32_e32 v3, v3, v4
	v_mul_f32_e32 v4, v39, v8
	v_mul_f32_e32 v4, v95, v4
	v_and_b32_e32 v5, 0xffff0000, v147
	v_mul_f32_e32 v4, v4, v5
	v_cvt_pk_bf16_f32 v38, v0, v2
	v_cvt_pk_bf16_f32 v39, v3, v4
	v_cvt_pk_bf16_f32 v2, v24, v25
	v_cvt_pk_bf16_f32 v3, v26, v27
	ds_write_b64 v230, v[2:3] offset:51200
	v_mul_f32_e32 v0, v15, v8
	s_waitcnt lgkmcnt(3)
	v_mul_f32_e32 v0, v96, v0
	v_lshlrev_b32_e32 v2, 16, v150
	v_mul_f32_e32 v0, v0, v2
	v_mul_f32_e32 v2, v50, v8
	v_mul_f32_e32 v2, v97, v2
	v_and_b32_e32 v3, 0xffff0000, v150
	v_mul_f32_e32 v2, v2, v3
	v_mul_f32_e32 v3, v51, v8
	v_mul_f32_e32 v3, v98, v3
	v_lshlrev_b32_e32 v4, 16, v151
	v_mul_f32_e32 v3, v3, v4
	v_mul_f32_e32 v4, v52, v8
	v_mul_f32_e32 v4, v99, v4
	v_and_b32_e32 v5, 0xffff0000, v151
	v_mul_f32_e32 v4, v4, v5
	v_cvt_pk_bf16_f32 v36, v0, v2
	v_cvt_pk_bf16_f32 v37, v3, v4
	v_cvt_pk_bf16_f32 v2, v28, v29
	v_cvt_pk_bf16_f32 v3, v30, v31
	ds_write_b64 v231, v[2:3] offset:51200
	s_nop 1
	v_permlane32_swap_b32_e32 v40, v42
	v_permlane32_swap_b32_e32 v41, v43
	v_permlane32_swap_b32_e32 v36, v38
	v_permlane32_swap_b32_e32 v37, v39
	global_store_dwordx4 v[6:7], v[40:43], off offset:-32
	global_store_dwordx4 v[6:7], v[36:39], off offset:-16
	s_cbranch_vccnz .LBB0_385
	ds_read2st64_b32 v[2:3], v184 offset1:1
	s_waitcnt lgkmcnt(0)
	v_add_f32_e32 v0, 0, v2
	v_add_f32_e32 v0, v0, v3
	ds_read2st64_b32 v[2:3], v184 offset0:2 offset1:3
	s_waitcnt lgkmcnt(0)
	v_add_f32_e32 v0, v0, v2
	v_add_f32_e32 v0, v0, v3
	ds_read2st64_b32 v[2:3], v184 offset0:4 offset1:5
	s_waitcnt lgkmcnt(0)
	v_add_f32_e32 v0, v0, v2
	v_add_f32_e32 v0, v0, v3
	ds_read2st64_b32 v[2:3], v184 offset0:6 offset1:7
	s_waitcnt lgkmcnt(0)
	v_add_f32_e32 v0, v0, v2
	v_add_f32_e32 v0, v0, v3
	v_fmac_f32_e32 v0, v223, v144
	v_mov_b32_e32 v223, v0
	ds_write_b32 v186, v0
